# conv: next-column loads issued two iterations ahead through two alternating staging register sets (loop unrolled by 2, uniform VMEM count, counted tail wait)
# baseline (speedup 1.0000x reference)
.LBB0_152:
	s_or_b64 exec, exec, s[34:35]
	v_lshl_add_u64 v[2:3], v[90:91], 1, s[18:19]
	v_lshl_add_u64 v[142:143], v[88:89], 1, v[2:3]
	global_load_dwordx4 v[128:131], v[142:143], off
	v_add_u32_e32 v234, 2, v116
	v_cmp_lt_u32_e64 s[40:41], v234, v233
	v_mov_b32_e32 v0, v1
	v_mov_b32_e32 v2, v1
	v_mov_b32_e32 v3, v1
	v_mov_b64_e32 v[244:245], v[0:1]
	v_mov_b64_e32 v[246:247], v[2:3]
	v_mov_b64_e32 v[248:249], v[0:1]
	v_mov_b64_e32 v[250:251], v[2:3]
	v_mov_b64_e32 v[150:151], v[0:1]
	v_mov_b64_e32 v[152:153], v[2:3]
	s_and_b64 s[42:43], s[28:29], s[40:41]
	s_and_saveexec_b64 s[38:39], s[42:43]
	s_cbranch_execz .Lcv_p0
	v_add_co_u32_e32 v2, vcc, 0xfffab000, v144
	s_nop 1
	v_addc_co_u32_e32 v3, vcc, -1, v145, vcc
	global_load_dwordx4 v[244:247], v[2:3], off offset:-1024
.Lcv_p0:
	s_or_b64 exec, exec, s[38:39]
	s_and_saveexec_b64 s[38:39], s[40:41]
	s_cbranch_execz .Lcv_p1
	v_add_co_u32_e32 v2, vcc, 0x2000, v144
	s_nop 1
	v_addc_co_u32_e32 v3, vcc, 0, v145, vcc
	global_load_dwordx4 v[248:251], v[2:3], off offset:3072
.Lcv_p1:
	s_or_b64 exec, exec, s[38:39]
	s_and_b64 s[42:43], s[30:31], s[40:41]
	s_and_saveexec_b64 s[38:39], s[42:43]
	s_cbranch_execz .Lcv_p2
	v_add_co_u32_e32 v2, vcc, 0x5a000, v144
	s_nop 1
	v_addc_co_u32_e32 v3, vcc, 0, v145, vcc
	global_load_dwordx4 v[150:153], v[2:3], off offset:3072
.Lcv_p2:
	s_or_b64 exec, exec, s[38:39]
	v_add_co_u32_e32 v2, vcc, 0xb581000, v144
	s_nop 1
	v_addc_co_u32_e32 v3, vcc, 0, v145, vcc
	global_load_dwordx4 v[154:157], v[2:3], off offset:1536
	v_add_u32_e32 v234, 1, v234
	s_mov_b64 s[34:35], 0
	s_waitcnt vmcnt(0)
.LBB0_153:
	v_mov_b64_e32 v[118:119], v[98:99]
	v_mov_b64_e32 v[116:117], v[96:97]
	v_mov_b64_e32 v[122:123], v[102:103]
	v_mov_b64_e32 v[126:127], v[94:95]
	v_mov_b64_e32 v[96:97], v[108:109]
	v_mov_b32_e32 v2, v1
	v_mov_b32_e32 v3, v1
	v_mov_b64_e32 v[120:121], v[100:101]
	v_mov_b64_e32 v[124:125], v[92:93]
	v_mov_b64_e32 v[98:99], v[110:111]
	v_mov_b64_e32 v[100:101], v[104:105]
	v_mov_b64_e32 v[94:95], v[78:79]
	v_cmp_lt_u32_e64 s[40:41], v234, v233
	v_mov_b32_e32 v0, v1
	v_mov_b64_e32 v[110:111], v[2:3]
	v_mov_b64_e32 v[102:103], v[106:107]
	v_mov_b64_e32 v[92:93], v[76:77]
	v_lshl_add_u64 v[162:163], v[144:145], 0, s[34:35]
	s_and_b64 s[42:43], s[28:29], s[40:41]
	v_mov_b64_e32 v[108:109], v[0:1]
	s_and_saveexec_b64 s[38:39], s[42:43]
	s_cbranch_execz .Lcv_d_E_155
	v_add_co_u32_e32 v76, vcc, 0xfffac600, v162
	s_nop 1
	v_addc_co_u32_e32 v77, vcc, -1, v163, vcc
	global_load_dwordx4 v[108:111], v[76:77], off offset:-1024
	s_branch .LBB0_155
.Lcv_d_E_155:
	s_or_b64 exec, exec, s[38:39]
	global_load_dword v235, v[162:163], off
.LBB0_155:
	s_or_b64 exec, exec, s[38:39]
	v_mov_b64_e32 v[106:107], v[2:3]
	v_mov_b64_e32 v[104:105], v[0:1]
	s_and_saveexec_b64 s[38:39], s[40:41]
	s_cbranch_execz .Lcv_d_E_157
	v_add_co_u32_e32 v2, vcc, 0x3600, v162
	s_nop 1
	v_addc_co_u32_e32 v3, vcc, 0, v163, vcc
	global_load_dwordx4 v[104:107], v[2:3], off offset:3072
	s_branch .LBB0_157

.LBB0_157:
	s_or_b64 exec, exec, s[38:39]
	v_mov_b32_e32 v2, v1
	v_mov_b32_e32 v3, v1
	v_mov_b32_e32 v0, v1
	v_mov_b64_e32 v[78:79], v[2:3]
	s_and_b64 s[40:41], s[30:31], s[40:41]
	v_mov_b64_e32 v[76:77], v[0:1]
	s_and_saveexec_b64 s[38:39], s[40:41]
	s_cbranch_execz .Lcv_d_E_159
	v_add_co_u32_e32 v2, vcc, 0x5b600, v162
	s_nop 1
	v_addc_co_u32_e32 v3, vcc, 0, v163, vcc
	global_load_dwordx4 v[76:79], v[2:3], off offset:3072
	s_branch .LBB0_159

.LBB0_159:
	s_or_b64 exec, exec, s[38:39]
	v_add_co_u32_e32 v2, vcc, 0xb582600, v162
	v_lshlrev_b32_e32 v172, 16, v116
	s_nop 0
	v_addc_co_u32_e32 v3, vcc, 0, v163, vcc
	global_load_dwordx4 v[88:91], v[2:3], off offset:1536
	v_lshlrev_b32_e32 v2, 16, v136
	v_and_b32_e32 v3, 0xffff0000, v136
	v_and_b32_e32 v173, 0xffff0000, v116
	v_pk_fma_f32 v[2:3], v[64:65], v[2:3], v[84:85]
	v_lshlrev_b32_e32 v174, 16, v96
	v_pk_fma_f32 v[236:237], v[72:73], v[172:173], v[2:3]
	v_and_b32_e32 v175, 0xffff0000, v96
	v_lshlrev_b32_e32 v238, 16, v132
	v_and_b32_e32 v239, 0xffff0000, v132
	v_pk_fma_f32 v[236:237], v[32:33], v[174:175], v[236:237]
	v_lshlrev_b32_e32 v182, 16, v120
	v_and_b32_e32 v183, 0xffff0000, v120
	v_pk_fma_f32 v[236:237], v[36:37], v[238:239], v[236:237]
	v_lshlrev_b32_e32 v188, 16, v100
	v_and_b32_e32 v189, 0xffff0000, v100
	v_pk_fma_f32 v[236:237], v[40:41], v[182:183], v[236:237]
	v_lshlrev_b32_e32 v238, 16, v112
	v_and_b32_e32 v239, 0xffff0000, v112
	v_pk_fma_f32 v[236:237], v[44:45], v[188:189], v[236:237]
	v_lshlrev_b32_e32 v190, 16, v124
	v_and_b32_e32 v191, 0xffff0000, v124
	v_pk_fma_f32 v[236:237], v[48:49], v[238:239], v[236:237]
	v_lshlrev_b32_e32 v194, 16, v92
	v_and_b32_e32 v195, 0xffff0000, v92
	v_pk_fma_f32 v[236:237], v[52:53], v[190:191], v[236:237]
	v_lshlrev_b32_e32 v238, 16, v128
	v_pk_fma_f32 v[236:237], v[56:57], v[194:195], v[236:237]
	v_and_b32_e32 v239, 0xffff0000, v128
	v_mul_f32_e32 v0, 0x3d372713, v236
	v_mul_f32_e32 v0, v236, v0
	v_fma_f32 v0, v236, v0, v236
	v_mul_f32_e32 v0, 0x40135761, v0
	v_exp_f32_e32 v242, v0
	v_mul_f32_e32 v0, 0x3d372713, v237
	v_mul_f32_e32 v0, v237, v0
	v_fma_f32 v0, v237, v0, v237
	v_mul_f32_e32 v0, 0x40135761, v0
	v_exp_f32_e32 v243, v0
	v_lshlrev_b32_e32 v2, 16, v137
	v_and_b32_e32 v3, 0xffff0000, v137
	v_lshlrev_b32_e32 v176, 16, v117
	v_pk_add_f32 v[242:243], v[242:243], 1.0 op_sel_hi:[1,0]
	v_and_b32_e32 v177, 0xffff0000, v117
	v_rcp_f32_e32 v243, v243
	v_pk_fma_f32 v[2:3], v[66:67], v[2:3], v[86:87]
	v_lshlrev_b32_e32 v178, 16, v97
	v_pk_fma_f32 v[204:205], v[74:75], v[176:177], v[2:3]
	v_fma_f32 v237, -v237, v243, v237
	v_rcp_f32_e32 v242, v242
	v_and_b32_e32 v179, 0xffff0000, v97
	v_lshlrev_b32_e32 v240, 16, v133
	v_and_b32_e32 v241, 0xffff0000, v133
	v_fma_f32 v236, -v236, v242, v236
	v_pk_fma_f32 v[204:205], v[34:35], v[178:179], v[204:205]
	v_lshlrev_b32_e32 v164, 16, v121
	v_and_b32_e32 v165, 0xffff0000, v121
	v_pk_fma_f32 v[204:205], v[38:39], v[240:241], v[204:205]
	v_lshlrev_b32_e32 v166, 16, v101
	v_and_b32_e32 v167, 0xffff0000, v101
	v_pk_mul_f32 v[236:237], v[236:237], v[238:239]
	v_pk_fma_f32 v[204:205], v[42:43], v[164:165], v[204:205]
	v_cvt_pk_bf16_f32 v112, v236, v237
	v_lshlrev_b32_e32 v236, 16, v113
	v_and_b32_e32 v237, 0xffff0000, v113
	v_pk_fma_f32 v[204:205], v[46:47], v[166:167], v[204:205]
	v_lshlrev_b32_e32 v168, 16, v125
	v_and_b32_e32 v169, 0xffff0000, v125
	v_pk_fma_f32 v[204:205], v[50:51], v[236:237], v[204:205]
	v_lshlrev_b32_e32 v170, 16, v93
	v_and_b32_e32 v171, 0xffff0000, v93
	v_pk_fma_f32 v[204:205], v[54:55], v[168:169], v[204:205]
	v_lshlrev_b32_e32 v2, 16, v138
	v_pk_fma_f32 v[204:205], v[58:59], v[170:171], v[204:205]
	v_and_b32_e32 v3, 0xffff0000, v138
	v_mul_f32_e32 v0, 0x3d372713, v204
	v_mul_f32_e32 v0, v204, v0
	v_fma_f32 v0, v204, v0, v204
	v_mul_f32_e32 v0, 0x40135761, v0
	v_exp_f32_e32 v236, v0
	v_mul_f32_e32 v0, 0x3d372713, v205
	v_mul_f32_e32 v0, v205, v0
	v_fma_f32 v0, v205, v0, v205
	v_mul_f32_e32 v0, 0x40135761, v0
	v_exp_f32_e32 v237, v0
	v_lshlrev_b32_e32 v180, 16, v118
	v_and_b32_e32 v181, 0xffff0000, v118
	v_pk_add_f32 v[236:237], v[236:237], 1.0 op_sel_hi:[1,0]
	v_pk_fma_f32 v[2:3], v[60:61], v[2:3], v[80:81]
	v_rcp_f32_e32 v237, v237
	v_lshlrev_b32_e32 v128, 16, v129
	v_and_b32_e32 v129, 0xffff0000, v129
	v_pk_fma_f32 v[200:201], v[68:69], v[180:181], v[2:3]
	v_fma_f32 v205, -v205, v237, v205
	v_rcp_f32_e32 v236, v236
	v_lshlrev_b32_e32 v184, 16, v98
	v_and_b32_e32 v185, 0xffff0000, v98
	v_lshlrev_b32_e32 v202, 16, v134
	v_fma_f32 v204, -v204, v236, v204
	v_and_b32_e32 v203, 0xffff0000, v134
	v_lshlrev_b32_e32 v2, 16, v139
	v_and_b32_e32 v3, 0xffff0000, v139
	v_pk_mul_f32 v[128:129], v[204:205], v[128:129]
	v_lshlrev_b32_e32 v138, 16, v122
	v_cvt_pk_bf16_f32 v113, v128, v129
	v_pk_fma_f32 v[128:129], v[4:5], v[184:185], v[200:201]
	v_and_b32_e32 v139, 0xffff0000, v122
	v_pk_fma_f32 v[128:129], v[8:9], v[202:203], v[128:129]
	v_lshlrev_b32_e32 v146, 16, v102
	v_and_b32_e32 v147, 0xffff0000, v102
	v_pk_fma_f32 v[128:129], v[12:13], v[138:139], v[128:129]
	v_lshlrev_b32_e32 v200, 16, v114
	v_and_b32_e32 v201, 0xffff0000, v114
	v_pk_fma_f32 v[128:129], v[16:17], v[146:147], v[128:129]
	v_lshlrev_b32_e32 v148, 16, v126
	v_and_b32_e32 v149, 0xffff0000, v126
	v_pk_fma_f32 v[128:129], v[20:21], v[200:201], v[128:129]
	v_lshlrev_b32_e32 v160, 16, v94
	v_and_b32_e32 v161, 0xffff0000, v94
	v_pk_fma_f32 v[128:129], v[24:25], v[148:149], v[128:129]
	v_lshlrev_b32_e32 v200, 16, v130
	v_pk_fma_f32 v[128:129], v[28:29], v[160:161], v[128:129]
	v_and_b32_e32 v201, 0xffff0000, v130
	v_mul_f32_e32 v0, 0x3d372713, v128
	v_mul_f32_e32 v0, v128, v0
	v_fma_f32 v0, v128, v0, v128
	v_mul_f32_e32 v0, 0x40135761, v0
	v_exp_f32_e32 v202, v0
	v_mul_f32_e32 v0, 0x3d372713, v129
	v_mul_f32_e32 v0, v129, v0
	v_fma_f32 v0, v129, v0, v129
	v_mul_f32_e32 v0, 0x40135761, v0
	v_exp_f32_e32 v203, v0
	v_lshlrev_b32_e32 v186, 16, v119
	v_and_b32_e32 v187, 0xffff0000, v119
	v_pk_add_f32 v[202:203], v[202:203], 1.0 op_sel_hi:[1,0]
	v_pk_fma_f32 v[2:3], v[62:63], v[2:3], v[82:83]
	v_rcp_f32_e32 v203, v203
	v_pk_fma_f32 v[196:197], v[70:71], v[186:187], v[2:3]
	v_lshlrev_b32_e32 v192, 16, v99
	v_and_b32_e32 v193, 0xffff0000, v99
	v_fma_f32 v129, -v129, v203, v129
	v_rcp_f32_e32 v202, v202
	v_lshlrev_b32_e32 v198, 16, v135
	v_and_b32_e32 v199, 0xffff0000, v135
	v_lshlrev_b32_e32 v2, 16, v123
	v_fma_f32 v128, -v128, v202, v128
	v_and_b32_e32 v3, 0xffff0000, v123
	v_lshlrev_b32_e32 v132, 16, v103
	v_and_b32_e32 v133, 0xffff0000, v103
	v_pk_mul_f32 v[128:129], v[128:129], v[200:201]
	v_lshlrev_b32_e32 v134, 16, v127
	v_cvt_pk_bf16_f32 v114, v128, v129
	v_pk_fma_f32 v[128:129], v[6:7], v[192:193], v[196:197]
	v_lshlrev_b32_e32 v196, 16, v115
	v_pk_fma_f32 v[128:129], v[10:11], v[198:199], v[128:129]
	v_and_b32_e32 v197, 0xffff0000, v115
	v_pk_fma_f32 v[128:129], v[14:15], v[2:3], v[128:129]
	v_and_b32_e32 v135, 0xffff0000, v127
	v_pk_fma_f32 v[128:129], v[18:19], v[132:133], v[128:129]
	v_lshlrev_b32_e32 v136, 16, v95
	v_pk_fma_f32 v[128:129], v[22:23], v[196:197], v[128:129]
	v_and_b32_e32 v137, 0xffff0000, v95
	v_pk_fma_f32 v[128:129], v[26:27], v[134:135], v[128:129]
	v_lshlrev_b32_e32 v130, 16, v131
	v_pk_fma_f32 v[128:129], v[30:31], v[136:137], v[128:129]
	v_and_b32_e32 v131, 0xffff0000, v131
	v_mul_f32_e32 v0, 0x3d372713, v128
	v_mul_f32_e32 v0, v128, v0
	v_fma_f32 v0, v128, v0, v128
	v_mul_f32_e32 v0, 0x40135761, v0
	v_exp_f32_e32 v196, v0
	v_mul_f32_e32 v0, 0x3d372713, v129
	v_mul_f32_e32 v0, v129, v0
	v_fma_f32 v0, v129, v0, v129
	v_mul_f32_e32 v0, 0x40135761, v0
	v_exp_f32_e32 v197, v0
	s_add_u32 s34, s34, 0x1600
	s_addc_u32 s35, s35, 0
	v_pk_add_f32 v[196:197], v[196:197], 1.0 op_sel_hi:[1,0]
	v_add_u32_e32 v234, 1, v234
	v_rcp_f32_e32 v197, v197
	s_cmp_eq_u32 s34, 0x2aa00
	v_fma_f32 v129, -v129, v197, v129
	v_rcp_f32_e32 v196, v196
	s_mov_b32 s38, 0xb580000
	v_fma_f32 v128, -v128, v196, v128
	s_nop 0
	v_pk_mul_f32 v[128:129], v[128:129], v[130:131]
	s_nop 0
	v_cvt_pk_bf16_f32 v115, v128, v129
	v_add_co_u32_e32 v128, vcc, s38, v162
	s_nop 1
	v_addc_co_u32_e32 v129, vcc, 0, v163, vcc
	global_store_dwordx4 v[128:129], v[112:115], off
	s_cbranch_scc1 .Lcv_exit_E
	s_nop 0
	v_mov_b64_e32 v[112:113], v[124:125]
	v_mov_b64_e32 v[134:135], v[122:123]
	v_mov_b64_e32 v[138:139], v[118:119]
	s_waitcnt vmcnt(6)
	v_mov_b64_e32 v[130:131], v[156:157]
	v_mov_b64_e32 v[114:115], v[126:127]
	v_mov_b64_e32 v[132:133], v[120:121]
	v_mov_b64_e32 v[136:137], v[116:117]
	v_mov_b64_e32 v[128:129], v[154:155]
	s_branch .Lcv_bodyO
.Lcv_bodyO:
	v_mov_b64_e32 v[118:119], v[98:99]
	v_mov_b64_e32 v[116:117], v[96:97]
	v_mov_b64_e32 v[122:123], v[102:103]
	v_mov_b64_e32 v[126:127], v[94:95]
	v_mov_b64_e32 v[96:97], v[244:245]
	v_mov_b32_e32 v2, v1
	v_mov_b32_e32 v3, v1
	v_mov_b64_e32 v[120:121], v[100:101]
	v_mov_b64_e32 v[124:125], v[92:93]
	v_mov_b64_e32 v[98:99], v[246:247]
	v_mov_b64_e32 v[100:101], v[248:249]
	v_mov_b64_e32 v[94:95], v[152:153]
	v_cmp_lt_u32_e64 s[40:41], v234, v233
	v_mov_b32_e32 v0, v1
	v_mov_b64_e32 v[246:247], v[2:3]
	v_mov_b64_e32 v[102:103], v[250:251]
	v_mov_b64_e32 v[92:93], v[150:151]
	v_lshl_add_u64 v[162:163], v[144:145], 0, s[34:35]
	s_and_b64 s[42:43], s[28:29], s[40:41]
	v_mov_b64_e32 v[244:245], v[0:1]
	s_and_saveexec_b64 s[38:39], s[42:43]
	s_cbranch_execz .Lcv_d_O_155
	v_add_co_u32_e32 v150, vcc, 0xfffac600, v162
	s_nop 1
	v_addc_co_u32_e32 v151, vcc, -1, v163, vcc
	global_load_dwordx4 v[244:247], v[150:151], off offset:-1024
	s_branch .Lcv_O_155

.Lcv_O_155:
	s_or_b64 exec, exec, s[38:39]
	v_mov_b64_e32 v[250:251], v[2:3]
	v_mov_b64_e32 v[248:249], v[0:1]
	s_and_saveexec_b64 s[38:39], s[40:41]
	s_cbranch_execz .Lcv_d_O_157
	v_add_co_u32_e32 v2, vcc, 0x3600, v162
	s_nop 1
	v_addc_co_u32_e32 v3, vcc, 0, v163, vcc
	global_load_dwordx4 v[248:251], v[2:3], off offset:3072
	s_branch .Lcv_O_157

.Lcv_O_157:
	s_or_b64 exec, exec, s[38:39]
	v_mov_b32_e32 v2, v1
	v_mov_b32_e32 v3, v1
	v_mov_b32_e32 v0, v1
	v_mov_b64_e32 v[152:153], v[2:3]
	s_and_b64 s[40:41], s[30:31], s[40:41]
	v_mov_b64_e32 v[150:151], v[0:1]
	s_and_saveexec_b64 s[38:39], s[40:41]
	s_cbranch_execz .Lcv_d_O_159
	v_add_co_u32_e32 v2, vcc, 0x5b600, v162
	s_nop 1
	v_addc_co_u32_e32 v3, vcc, 0, v163, vcc
	global_load_dwordx4 v[150:153], v[2:3], off offset:3072
	s_branch .Lcv_O_159

.Lcv_O_159:
	s_or_b64 exec, exec, s[38:39]
	v_add_co_u32_e32 v2, vcc, 0xb582600, v162
	v_lshlrev_b32_e32 v172, 16, v116
	s_nop 0
	v_addc_co_u32_e32 v3, vcc, 0, v163, vcc
	global_load_dwordx4 v[154:157], v[2:3], off offset:1536
	v_lshlrev_b32_e32 v2, 16, v136
	v_and_b32_e32 v3, 0xffff0000, v136
	v_and_b32_e32 v173, 0xffff0000, v116
	v_pk_fma_f32 v[2:3], v[64:65], v[2:3], v[84:85]
	v_lshlrev_b32_e32 v174, 16, v96
	v_pk_fma_f32 v[236:237], v[72:73], v[172:173], v[2:3]
	v_and_b32_e32 v175, 0xffff0000, v96
	v_lshlrev_b32_e32 v238, 16, v132
	v_and_b32_e32 v239, 0xffff0000, v132
	v_pk_fma_f32 v[236:237], v[32:33], v[174:175], v[236:237]
	v_lshlrev_b32_e32 v182, 16, v120
	v_and_b32_e32 v183, 0xffff0000, v120
	v_pk_fma_f32 v[236:237], v[36:37], v[238:239], v[236:237]
	v_lshlrev_b32_e32 v188, 16, v100
	v_and_b32_e32 v189, 0xffff0000, v100
	v_pk_fma_f32 v[236:237], v[40:41], v[182:183], v[236:237]
	v_lshlrev_b32_e32 v238, 16, v112
	v_and_b32_e32 v239, 0xffff0000, v112
	v_pk_fma_f32 v[236:237], v[44:45], v[188:189], v[236:237]
	v_lshlrev_b32_e32 v190, 16, v124
	v_and_b32_e32 v191, 0xffff0000, v124
	v_pk_fma_f32 v[236:237], v[48:49], v[238:239], v[236:237]
	v_lshlrev_b32_e32 v194, 16, v92
	v_and_b32_e32 v195, 0xffff0000, v92
	v_pk_fma_f32 v[236:237], v[52:53], v[190:191], v[236:237]
	v_lshlrev_b32_e32 v238, 16, v128
	v_pk_fma_f32 v[236:237], v[56:57], v[194:195], v[236:237]
	v_and_b32_e32 v239, 0xffff0000, v128
	v_mul_f32_e32 v0, 0x3d372713, v236
	v_mul_f32_e32 v0, v236, v0
	v_fma_f32 v0, v236, v0, v236
	v_mul_f32_e32 v0, 0x40135761, v0
	v_exp_f32_e32 v242, v0
	v_mul_f32_e32 v0, 0x3d372713, v237
	v_mul_f32_e32 v0, v237, v0
	v_fma_f32 v0, v237, v0, v237
	v_mul_f32_e32 v0, 0x40135761, v0
	v_exp_f32_e32 v243, v0
	v_lshlrev_b32_e32 v2, 16, v137
	v_and_b32_e32 v3, 0xffff0000, v137
	v_lshlrev_b32_e32 v176, 16, v117
	v_pk_add_f32 v[242:243], v[242:243], 1.0 op_sel_hi:[1,0]
	v_and_b32_e32 v177, 0xffff0000, v117
	v_rcp_f32_e32 v243, v243
	v_pk_fma_f32 v[2:3], v[66:67], v[2:3], v[86:87]
	v_lshlrev_b32_e32 v178, 16, v97
	v_pk_fma_f32 v[204:205], v[74:75], v[176:177], v[2:3]
	v_fma_f32 v237, -v237, v243, v237
	v_rcp_f32_e32 v242, v242
	v_and_b32_e32 v179, 0xffff0000, v97
	v_lshlrev_b32_e32 v240, 16, v133
	v_and_b32_e32 v241, 0xffff0000, v133
	v_fma_f32 v236, -v236, v242, v236
	v_pk_fma_f32 v[204:205], v[34:35], v[178:179], v[204:205]
	v_lshlrev_b32_e32 v164, 16, v121
	v_and_b32_e32 v165, 0xffff0000, v121
	v_pk_fma_f32 v[204:205], v[38:39], v[240:241], v[204:205]
	v_lshlrev_b32_e32 v166, 16, v101
	v_and_b32_e32 v167, 0xffff0000, v101
	v_pk_mul_f32 v[236:237], v[236:237], v[238:239]
	v_pk_fma_f32 v[204:205], v[42:43], v[164:165], v[204:205]
	v_cvt_pk_bf16_f32 v112, v236, v237
	v_lshlrev_b32_e32 v236, 16, v113
	v_and_b32_e32 v237, 0xffff0000, v113
	v_pk_fma_f32 v[204:205], v[46:47], v[166:167], v[204:205]
	v_lshlrev_b32_e32 v168, 16, v125
	v_and_b32_e32 v169, 0xffff0000, v125
	v_pk_fma_f32 v[204:205], v[50:51], v[236:237], v[204:205]
	v_lshlrev_b32_e32 v170, 16, v93
	v_and_b32_e32 v171, 0xffff0000, v93
	v_pk_fma_f32 v[204:205], v[54:55], v[168:169], v[204:205]
	v_lshlrev_b32_e32 v2, 16, v138
	v_pk_fma_f32 v[204:205], v[58:59], v[170:171], v[204:205]
	v_and_b32_e32 v3, 0xffff0000, v138
	v_mul_f32_e32 v0, 0x3d372713, v204
	v_mul_f32_e32 v0, v204, v0
	v_fma_f32 v0, v204, v0, v204
	v_mul_f32_e32 v0, 0x40135761, v0
	v_exp_f32_e32 v236, v0
	v_mul_f32_e32 v0, 0x3d372713, v205
	v_mul_f32_e32 v0, v205, v0
	v_fma_f32 v0, v205, v0, v205
	v_mul_f32_e32 v0, 0x40135761, v0
	v_exp_f32_e32 v237, v0
	v_lshlrev_b32_e32 v180, 16, v118
	v_and_b32_e32 v181, 0xffff0000, v118
	v_pk_add_f32 v[236:237], v[236:237], 1.0 op_sel_hi:[1,0]
	v_pk_fma_f32 v[2:3], v[60:61], v[2:3], v[80:81]
	v_rcp_f32_e32 v237, v237
	v_lshlrev_b32_e32 v128, 16, v129
	v_and_b32_e32 v129, 0xffff0000, v129
	v_pk_fma_f32 v[200:201], v[68:69], v[180:181], v[2:3]
	v_fma_f32 v205, -v205, v237, v205
	v_rcp_f32_e32 v236, v236
	v_lshlrev_b32_e32 v184, 16, v98
	v_and_b32_e32 v185, 0xffff0000, v98
	v_lshlrev_b32_e32 v202, 16, v134
	v_fma_f32 v204, -v204, v236, v204
	v_and_b32_e32 v203, 0xffff0000, v134
	v_lshlrev_b32_e32 v2, 16, v139
	v_and_b32_e32 v3, 0xffff0000, v139
	v_pk_mul_f32 v[128:129], v[204:205], v[128:129]
	v_lshlrev_b32_e32 v138, 16, v122
	v_cvt_pk_bf16_f32 v113, v128, v129
	v_pk_fma_f32 v[128:129], v[4:5], v[184:185], v[200:201]
	v_and_b32_e32 v139, 0xffff0000, v122
	v_pk_fma_f32 v[128:129], v[8:9], v[202:203], v[128:129]
	v_lshlrev_b32_e32 v146, 16, v102
	v_and_b32_e32 v147, 0xffff0000, v102
	v_pk_fma_f32 v[128:129], v[12:13], v[138:139], v[128:129]
	v_lshlrev_b32_e32 v200, 16, v114
	v_and_b32_e32 v201, 0xffff0000, v114
	v_pk_fma_f32 v[128:129], v[16:17], v[146:147], v[128:129]
	v_lshlrev_b32_e32 v148, 16, v126
	v_and_b32_e32 v149, 0xffff0000, v126
	v_pk_fma_f32 v[128:129], v[20:21], v[200:201], v[128:129]
	v_lshlrev_b32_e32 v160, 16, v94
	v_and_b32_e32 v161, 0xffff0000, v94
	v_pk_fma_f32 v[128:129], v[24:25], v[148:149], v[128:129]
	v_lshlrev_b32_e32 v200, 16, v130
	v_pk_fma_f32 v[128:129], v[28:29], v[160:161], v[128:129]
	v_and_b32_e32 v201, 0xffff0000, v130
	v_mul_f32_e32 v0, 0x3d372713, v128
	v_mul_f32_e32 v0, v128, v0
	v_fma_f32 v0, v128, v0, v128
	v_mul_f32_e32 v0, 0x40135761, v0
	v_exp_f32_e32 v202, v0
	v_mul_f32_e32 v0, 0x3d372713, v129
	v_mul_f32_e32 v0, v129, v0
	v_fma_f32 v0, v129, v0, v129
	v_mul_f32_e32 v0, 0x40135761, v0
	v_exp_f32_e32 v203, v0
	v_lshlrev_b32_e32 v186, 16, v119
	v_and_b32_e32 v187, 0xffff0000, v119
	v_pk_add_f32 v[202:203], v[202:203], 1.0 op_sel_hi:[1,0]
	v_pk_fma_f32 v[2:3], v[62:63], v[2:3], v[82:83]
	v_rcp_f32_e32 v203, v203
	v_pk_fma_f32 v[196:197], v[70:71], v[186:187], v[2:3]
	v_lshlrev_b32_e32 v192, 16, v99
	v_and_b32_e32 v193, 0xffff0000, v99
	v_fma_f32 v129, -v129, v203, v129
	v_rcp_f32_e32 v202, v202
	v_lshlrev_b32_e32 v198, 16, v135
	v_and_b32_e32 v199, 0xffff0000, v135
	v_lshlrev_b32_e32 v2, 16, v123
	v_fma_f32 v128, -v128, v202, v128
	v_and_b32_e32 v3, 0xffff0000, v123
	v_lshlrev_b32_e32 v132, 16, v103
	v_and_b32_e32 v133, 0xffff0000, v103
	v_pk_mul_f32 v[128:129], v[128:129], v[200:201]
	v_lshlrev_b32_e32 v134, 16, v127
	v_cvt_pk_bf16_f32 v114, v128, v129
	v_pk_fma_f32 v[128:129], v[6:7], v[192:193], v[196:197]
	v_lshlrev_b32_e32 v196, 16, v115
	v_pk_fma_f32 v[128:129], v[10:11], v[198:199], v[128:129]
	v_and_b32_e32 v197, 0xffff0000, v115
	v_pk_fma_f32 v[128:129], v[14:15], v[2:3], v[128:129]
	v_and_b32_e32 v135, 0xffff0000, v127
	v_pk_fma_f32 v[128:129], v[18:19], v[132:133], v[128:129]
	v_lshlrev_b32_e32 v136, 16, v95
	v_pk_fma_f32 v[128:129], v[22:23], v[196:197], v[128:129]
	v_and_b32_e32 v137, 0xffff0000, v95
	v_pk_fma_f32 v[128:129], v[26:27], v[134:135], v[128:129]
	v_lshlrev_b32_e32 v130, 16, v131
	v_pk_fma_f32 v[128:129], v[30:31], v[136:137], v[128:129]
	v_and_b32_e32 v131, 0xffff0000, v131
	v_mul_f32_e32 v0, 0x3d372713, v128
	v_mul_f32_e32 v0, v128, v0
	v_fma_f32 v0, v128, v0, v128
	v_mul_f32_e32 v0, 0x40135761, v0
	v_exp_f32_e32 v196, v0
	v_mul_f32_e32 v0, 0x3d372713, v129
	v_mul_f32_e32 v0, v129, v0
	v_fma_f32 v0, v129, v0, v129
	v_mul_f32_e32 v0, 0x40135761, v0
	v_exp_f32_e32 v197, v0
	s_add_u32 s34, s34, 0x1600
	s_addc_u32 s35, s35, 0
	v_pk_add_f32 v[196:197], v[196:197], 1.0 op_sel_hi:[1,0]
	v_add_u32_e32 v234, 1, v234
	v_rcp_f32_e32 v197, v197
	s_cmp_eq_u32 s34, 0x2aa00
	v_fma_f32 v129, -v129, v197, v129
	v_rcp_f32_e32 v196, v196
	s_mov_b32 s38, 0xb580000
	v_fma_f32 v128, -v128, v196, v128
	s_nop 0
	v_pk_mul_f32 v[128:129], v[128:129], v[130:131]
	s_nop 0
	v_cvt_pk_bf16_f32 v115, v128, v129
	v_add_co_u32_e32 v128, vcc, s38, v162
	s_nop 1
	v_addc_co_u32_e32 v129, vcc, 0, v163, vcc
	global_store_dwordx4 v[128:129], v[112:115], off
	s_cbranch_scc1 .Lcv_exit_O
	s_nop 0
	v_mov_b64_e32 v[112:113], v[124:125]
	v_mov_b64_e32 v[134:135], v[122:123]
	v_mov_b64_e32 v[138:139], v[118:119]
	s_waitcnt vmcnt(6)
	v_mov_b64_e32 v[130:131], v[90:91]
	v_mov_b64_e32 v[114:115], v[126:127]
	v_mov_b64_e32 v[132:133], v[120:121]
	v_mov_b64_e32 v[136:137], v[116:117]
	v_mov_b64_e32 v[128:129], v[88:89]
	s_branch .LBB0_153
.Lcv_exit_E:
	s_waitcnt vmcnt(0)
	v_mov_b64_e32 v[108:109], v[244:245]
	v_mov_b64_e32 v[110:111], v[246:247]
	v_mov_b64_e32 v[104:105], v[248:249]
	v_mov_b64_e32 v[106:107], v[250:251]
	v_mov_b64_e32 v[76:77], v[150:151]
	v_mov_b64_e32 v[78:79], v[152:153]
	v_mov_b64_e32 v[88:89], v[154:155]
	v_mov_b64_e32 v[90:91], v[156:157]
	s_branch .LBB0_131
.Lcv_exit_O:
	s_waitcnt vmcnt(0)
	s_branch .LBB0_131
.LBB0_161:
	s_or_b64 exec, exec, s[14:15]
	v_mov_b64_e32 v[150:151], 0x200
	v_mov_b64_e32 v[152:153], 0x1ff
	v_mov_b64_e32 v[154:155], 0x62f
	v_mov_b64_e32 v[156:157], 0x630
	s_movk_i32 s27, 0x5ff
	v_readlane_b32 s28, v254, 62
	s_cmp_eq_u32 s86, 10
	s_cbranch_scc0 .LBB0_166
	s_cmp_eq_u32 s56, 0x100
	s_cbranch_scc0 .Lconv_tail_orig
	s_cmp_eq_u32 s99, 1
	s_cbranch_scc1 .Lconv_tail_done2
	s_mov_b32 s98, 22
	s_cmp_lt_i32 s0, 16
	s_cbranch_scc1 .Lconv_ctx_gemm
	s_cmp_lt_i32 s0, 22
	s_cbranch_scc0 .LBB0_166
	s_waitcnt vmcnt(0) lgkmcnt(0)
	s_barrier
	v_cmp_eq_u32_e32 vcc, 0, v158
	s_and_saveexec_b64 s[8:9], vcc
	s_cbranch_execz .Lconv_arr_done
	s_load_dwordx2 s[10:11], s[54:55], 0x168
	buffer_wbl2 sc1
	s_waitcnt lgkmcnt(0)
	s_waitcnt vmcnt(0)
	s_add_u32 s10, s10, 0x3900
	s_addc_u32 s11, s11, 0
	v_mov_b32_e32 v0, 1
	s_nop 4
	global_atomic_add v1, v0, s[10:11]
